# queue index prefetch also under the context scan items' state-store epilogue (prefetch register v255)
# speedup vs baseline: 1.0074x; 1.0004x over previous
.LBB0_524:
	s_and_saveexec_b64 s[6:7], s[4:5]
	s_cbranch_execz .LBB0_528
	s_mov_b64 s[10:11], exec
	v_mbcnt_lo_u32_b32 v0, s10, 0
	v_mbcnt_hi_u32_b32 v0, s11, v0
	v_cmp_eq_u32_e32 vcc, 0, v0
	s_and_saveexec_b64 s[8:9], vcc
	s_cbranch_execz .LBB0_527
	v_readlane_b32 s0, v251, 20
	s_cmp_eq_u32 s0, 0
	s_cbranch_scc1 .Lq_nopf
	v_writelane_b32 v251, 0, 20
	s_waitcnt vmcnt(0)
	v_mov_b32_e32 v1, v255
	s_branch .LBB0_527

.Lam_nodma_b:
	s_sub_i32 s13, s13, 2
	s_cmp_gt_u32 s13, 0
	s_cbranch_scc1 .Lam_loop
	s_mov_b64 s[8:9], exec
	s_and_b64 exec, exec, s[4:5]
	s_cbranch_execz .Lam_pfx
	v_mov_b32_e32 v255, 1
	global_atomic_add v255, v97, v255, s[66:67] sc0

.LBB0_568:
	s_and_b64 vcc, exec, s[8:9]
	s_brev_b32 s30, 64
	v_readlane_b32 s31, v254, 63
	s_cbranch_vccz .LBB0_522
	s_cmp_lg_u32 s84, 0
	s_cbranch_scc1 .Lsc_pfx
	s_mov_b64 exec, 1
	v_mov_b32_e32 v255, 1
	global_atomic_add v255, v97, v255, s[66:67] sc0
	s_mov_b64 exec, -1
.Lsc_pfx:
	v_writelane_b32 v251, 1, 20
	s_mov_b32 s1, s93
	s_and_b64 s[8:9], s[10:11], exec
	v_mbcnt_lo_u32_b32 v96, -1, s1
	s_mov_b32 s1, 0x16000000
	s_cselect_b32 s1, s1, 0x1e000000
	s_add_u32 s1, s64, s1
	s_addc_u32 s8, s65, 0
	s_lshl_b64 s[6:7], s[6:7], 2
	s_add_u32 s1, s1, s6
	s_addc_u32 s6, s8, s7
	s_lshl_b32 s0, s0, 2
	v_mbcnt_hi_u32_b32 v96, -1, v96
	s_add_u32 s0, s1, s0
	v_or_b32_e32 v132, s84, v96
	s_addc_u32 s1, s6, 0
	v_readlane_b32 s6, v253, 11
	v_readlane_b32 s7, v253, 12
	v_and_b32_e32 v96, 15, v132
	s_add_u32 s0, s0, s6
	s_addc_u32 s1, s1, s7
	v_lshlrev_b32_e32 v96, 2, v96
	v_lshl_add_u64 v[98:99], s[0:1], 0, v[96:97]
	v_lshlrev_b32_e32 v96, 9, v132
	v_and_b32_e32 v96, 0x6000, v96
	v_lshl_add_u64 v[98:99], v[98:99], 0, v[96:97]
	global_store_dword v[98:99], v4, off nt
	global_store_dword v[98:99], v0, off offset:64 nt
	global_store_dword v[98:99], v5, off offset:2048 nt
	global_store_dword v[98:99], v1, off offset:2112 nt
	v_add_co_u32_e32 v0, vcc, s61, v98
	s_mov_b32 s0, 0x8000
	s_nop 0
	v_addc_co_u32_e32 v1, vcc, 0, v99, vcc
	global_store_dword v[0:1], v6, off nt
	global_store_dword v[0:1], v2, off offset:64 nt
	global_store_dword v[0:1], v7, off offset:2048 nt
	global_store_dword v[0:1], v3, off offset:2112 nt
	v_add_co_u32_e32 v0, vcc, s0, v98
	s_mov_b32 s0, 0x9000
	s_nop 0
	v_addc_co_u32_e32 v1, vcc, 0, v99, vcc
	v_add_co_u32_e32 v2, vcc, s0, v98
	s_mov_b32 s0, 0x11000
	s_nop 0
	v_addc_co_u32_e32 v3, vcc, 0, v99, vcc
	global_store_dword v[2:3], v52, off offset:-4096 nt
	global_store_dword v[0:1], v48, off offset:64 nt
	global_store_dword v[0:1], v53, off offset:2048 nt
	global_store_dword v[0:1], v49, off offset:2112 nt
	global_store_dword v[2:3], v54, off nt
	global_store_dword v[2:3], v50, off offset:64 nt
	global_store_dword v[2:3], v55, off offset:2048 nt
	global_store_dword v[2:3], v51, off offset:2112 nt
	v_add_co_u32_e32 v0, vcc, s96, v98
	s_nop 1
	v_addc_co_u32_e32 v1, vcc, 0, v99, vcc
	v_add_co_u32_e32 v2, vcc, s0, v98
	s_mov_b32 s0, 0x18000
	s_nop 0
	v_addc_co_u32_e32 v3, vcc, 0, v99, vcc
	global_store_dword v[2:3], v12, off offset:-4096 nt
	global_store_dword v[0:1], v8, off offset:64 nt
	global_store_dword v[0:1], v13, off offset:2048 nt
	global_store_dword v[0:1], v9, off offset:2112 nt
	global_store_dword v[2:3], v14, off nt
	global_store_dword v[2:3], v10, off offset:64 nt
	global_store_dword v[2:3], v15, off offset:2048 nt
	global_store_dword v[2:3], v11, off offset:2112 nt
	v_add_co_u32_e32 v0, vcc, s0, v98
	s_mov_b32 s0, 0x19000
	s_nop 0
	v_addc_co_u32_e32 v1, vcc, 0, v99, vcc
	v_add_co_u32_e32 v2, vcc, s0, v98
	s_mov_b32 s0, 0x20000
	s_nop 0
	v_addc_co_u32_e32 v3, vcc, 0, v99, vcc
	global_store_dword v[2:3], v36, off offset:-4096 nt
	global_store_dword v[0:1], v32, off offset:64 nt
	global_store_dword v[0:1], v37, off offset:2048 nt
	global_store_dword v[0:1], v33, off offset:2112 nt
	global_store_dword v[2:3], v38, off nt
	global_store_dword v[2:3], v34, off offset:64 nt
	global_store_dword v[2:3], v39, off offset:2048 nt
	global_store_dword v[2:3], v35, off offset:2112 nt
	v_add_co_u32_e32 v0, vcc, s0, v98
	s_mov_b32 s0, 0x21000
	s_nop 0
	v_addc_co_u32_e32 v1, vcc, 0, v99, vcc
	v_add_co_u32_e32 v2, vcc, s0, v98
	s_mov_b32 s0, 0x31000
	s_nop 0
	v_addc_co_u32_e32 v3, vcc, 0, v99, vcc
	global_store_dword v[2:3], v20, off offset:-4096 nt
	global_store_dword v[0:1], v16, off offset:64 nt
	global_store_dword v[0:1], v21, off offset:2048 nt
	global_store_dword v[0:1], v17, off offset:2112 nt
	global_store_dword v[2:3], v22, off nt
	global_store_dword v[2:3], v18, off offset:64 nt
	global_store_dword v[2:3], v23, off offset:2048 nt
	global_store_dword v[2:3], v19, off offset:2112 nt
	v_add_co_u32_e32 v0, vcc, s75, v98
	s_nop 1
	v_addc_co_u32_e32 v1, vcc, 0, v99, vcc
	v_add_co_u32_e32 v2, vcc, s2, v98
	s_nop 1
	v_addc_co_u32_e32 v3, vcc, 0, v99, vcc
	global_store_dword v[2:3], v60, off offset:-4096 nt
	global_store_dword v[0:1], v56, off offset:64 nt
	global_store_dword v[0:1], v61, off offset:2048 nt
	global_store_dword v[0:1], v57, off offset:2112 nt
	global_store_dword v[2:3], v62, off nt
	global_store_dword v[2:3], v58, off offset:64 nt
	global_store_dword v[2:3], v63, off offset:2048 nt
	global_store_dword v[2:3], v59, off offset:2112 nt
	v_add_co_u32_e32 v0, vcc, s91, v98
	s_nop 1
	v_addc_co_u32_e32 v1, vcc, 0, v99, vcc
	v_add_co_u32_e32 v2, vcc, s0, v98
	s_mov_b32 s0, 0x38000
	s_nop 0
	v_addc_co_u32_e32 v3, vcc, 0, v99, vcc
	global_store_dword v[2:3], v28, off offset:-4096 nt
	global_store_dword v[0:1], v24, off offset:64 nt
	global_store_dword v[0:1], v29, off offset:2048 nt
	global_store_dword v[0:1], v25, off offset:2112 nt
	global_store_dword v[2:3], v30, off nt
	global_store_dword v[2:3], v26, off offset:64 nt
	global_store_dword v[2:3], v31, off offset:2048 nt
	global_store_dword v[2:3], v27, off offset:2112 nt
	v_add_co_u32_e32 v0, vcc, s0, v98
	s_mov_b32 s0, 0x39000
	s_nop 0
	v_addc_co_u32_e32 v1, vcc, 0, v99, vcc
	v_add_co_u32_e32 v2, vcc, s0, v98
	s_mov_b32 s0, 0x40000
	s_nop 0
	v_addc_co_u32_e32 v3, vcc, 0, v99, vcc
	global_store_dword v[2:3], v76, off offset:-4096 nt
	global_store_dword v[0:1], v72, off offset:64 nt
	global_store_dword v[0:1], v77, off offset:2048 nt
	global_store_dword v[0:1], v73, off offset:2112 nt
	global_store_dword v[2:3], v78, off nt
	global_store_dword v[2:3], v74, off offset:64 nt
	global_store_dword v[2:3], v79, off offset:2048 nt
	global_store_dword v[2:3], v75, off offset:2112 nt
	v_add_co_u32_e32 v0, vcc, s0, v98
	s_mov_b32 s0, 0x41000
	s_nop 0
	v_addc_co_u32_e32 v1, vcc, 0, v99, vcc
	v_add_co_u32_e32 v2, vcc, s0, v98
	s_mov_b32 s0, 0x48000
	s_nop 0
	v_addc_co_u32_e32 v3, vcc, 0, v99, vcc
	global_store_dword v[2:3], v44, off offset:-4096 nt
	global_store_dword v[0:1], v40, off offset:64 nt
	global_store_dword v[0:1], v45, off offset:2048 nt
	global_store_dword v[0:1], v41, off offset:2112 nt
	global_store_dword v[2:3], v46, off nt
	global_store_dword v[2:3], v42, off offset:64 nt
	global_store_dword v[2:3], v47, off offset:2048 nt
	global_store_dword v[2:3], v43, off offset:2112 nt
	v_add_co_u32_e32 v0, vcc, s0, v98
	s_mov_b32 s0, 0x49000
	s_nop 0
	v_addc_co_u32_e32 v1, vcc, 0, v99, vcc
	v_add_co_u32_e32 v2, vcc, s0, v98
	s_mov_b32 s0, 0x58000
	s_nop 0
	v_addc_co_u32_e32 v3, vcc, 0, v99, vcc
	global_store_dword v[2:3], v100, off offset:-4096 nt
	global_store_dword v[0:1], v88, off offset:64 nt
	global_store_dword v[0:1], v101, off offset:2048 nt
	global_store_dword v[0:1], v89, off offset:2112 nt
	global_store_dword v[2:3], v102, off nt
	global_store_dword v[2:3], v90, off offset:64 nt
	global_store_dword v[2:3], v103, off offset:2048 nt
	global_store_dword v[2:3], v91, off offset:2112 nt
	v_add_co_u32_e32 v0, vcc, s70, v98
	s_nop 1
	v_addc_co_u32_e32 v1, vcc, 0, v99, vcc
	v_add_co_u32_e32 v2, vcc, s51, v98
	s_nop 1
	v_addc_co_u32_e32 v3, vcc, 0, v99, vcc
	global_store_dword v[2:3], v68, off offset:-4096 nt
	global_store_dword v[0:1], v64, off offset:64 nt
	global_store_dword v[0:1], v69, off offset:2048 nt
	global_store_dword v[0:1], v65, off offset:2112 nt
	global_store_dword v[2:3], v70, off nt
	global_store_dword v[2:3], v66, off offset:64 nt
	global_store_dword v[2:3], v71, off offset:2048 nt
	global_store_dword v[2:3], v67, off offset:2112 nt
	v_add_co_u32_e32 v0, vcc, s0, v98
	s_mov_b32 s0, 0x59000
	s_nop 0
	v_addc_co_u32_e32 v1, vcc, 0, v99, vcc
	v_add_co_u32_e32 v2, vcc, s0, v98
	s_mov_b32 s0, 0x60000
	s_nop 0
	v_addc_co_u32_e32 v3, vcc, 0, v99, vcc
	global_store_dword v[2:3], v112, off offset:-4096 nt
	global_store_dword v[0:1], v108, off offset:64 nt
	global_store_dword v[0:1], v113, off offset:2048 nt
	global_store_dword v[0:1], v109, off offset:2112 nt
	global_store_dword v[2:3], v114, off nt
	global_store_dword v[2:3], v110, off offset:64 nt
	global_store_dword v[2:3], v115, off offset:2048 nt
	global_store_dword v[2:3], v111, off offset:2112 nt
	v_add_co_u32_e32 v0, vcc, s0, v98
	s_mov_b32 s0, 0x61000
	s_nop 0
	v_addc_co_u32_e32 v1, vcc, 0, v99, vcc
	v_add_co_u32_e32 v2, vcc, s0, v98
	s_mov_b32 s0, 0x68000
	s_nop 0
	v_addc_co_u32_e32 v3, vcc, 0, v99, vcc
	global_store_dword v[2:3], v84, off offset:-4096 nt
	global_store_dword v[0:1], v80, off offset:64 nt
	global_store_dword v[0:1], v85, off offset:2048 nt
	global_store_dword v[0:1], v81, off offset:2112 nt
	global_store_dword v[2:3], v86, off nt
	global_store_dword v[2:3], v82, off offset:64 nt
	global_store_dword v[2:3], v87, off offset:2048 nt
	global_store_dword v[2:3], v83, off offset:2112 nt
	v_add_co_u32_e32 v0, vcc, s0, v98
	s_mov_b32 s0, 0x69000
	s_nop 0
	v_addc_co_u32_e32 v1, vcc, 0, v99, vcc
	v_add_co_u32_e32 v2, vcc, s0, v98
	s_mov_b32 s0, 0x70000
	s_nop 0
	v_addc_co_u32_e32 v3, vcc, 0, v99, vcc
	global_store_dword v[2:3], v120, off offset:-4096 nt
	global_store_dword v[0:1], v116, off offset:64 nt
	global_store_dword v[0:1], v121, off offset:2048 nt
	global_store_dword v[0:1], v117, off offset:2112 nt
	global_store_dword v[2:3], v122, off nt
	global_store_dword v[2:3], v118, off offset:64 nt
	global_store_dword v[2:3], v123, off offset:2048 nt
	global_store_dword v[2:3], v119, off offset:2112 nt
	v_add_co_u32_e32 v0, vcc, s0, v98
	s_mov_b32 s0, 0x71000
	s_nop 0
	v_addc_co_u32_e32 v1, vcc, 0, v99, vcc
	v_add_co_u32_e32 v2, vcc, s0, v98
	s_nop 1
	v_addc_co_u32_e32 v3, vcc, 0, v99, vcc
	global_store_dword v[2:3], v104, off offset:-4096 nt
	global_store_dword v[0:1], v92, off offset:64 nt
	global_store_dword v[0:1], v105, off offset:2048 nt
	global_store_dword v[0:1], v93, off offset:2112 nt
	global_store_dword v[2:3], v106, off nt
	global_store_dword v[2:3], v94, off offset:64 nt
	global_store_dword v[2:3], v107, off offset:2048 nt
	global_store_dword v[2:3], v95, off offset:2112 nt
	v_add_co_u32_e32 v0, vcc, s60, v98
	s_nop 1
	v_addc_co_u32_e32 v1, vcc, 0, v99, vcc
	global_store_dword v[0:1], v124, off nt
	global_store_dword v[0:1], v128, off offset:64 nt
	global_store_dword v[0:1], v125, off offset:2048 nt
	global_store_dword v[0:1], v129, off offset:2112 nt
	v_add_co_u32_e32 v0, vcc, 0x79000, v98
	s_nop 1
	v_addc_co_u32_e32 v1, vcc, 0, v99, vcc
	global_store_dword v[0:1], v126, off nt
	global_store_dword v[0:1], v130, off offset:64 nt
	global_store_dword v[0:1], v127, off offset:2048 nt
	global_store_dword v[0:1], v131, off offset:2112 nt
	s_branch .LBB0_522
